# attention near-diagonal bias path: dead index clamp removed, 16 bias gathers from one base with immediate offsets (47 fewer VALU per such tile); on top of v193
# speedup vs baseline: 1.0009x; 1.0009x over previous
.Latt_v_done:
	s_cmpk_lt_i32 s50, 0xffa6
	s_cbranch_scc1 .LBB0_1123
	v_add_u32_e32 v2, s50, v161
	v_lshl_add_u32 v165, v2, 2, s81
	ds_read_b32 v166, v165 offset:516
	ds_read_b32 v167, v165 offset:520
	ds_read_b32 v168, v165 offset:524
	ds_read_b32 v169, v165 offset:528
	ds_read_b32 v170, v165 offset:532
	ds_read_b32 v171, v165 offset:536
	ds_read_b32 v172, v165 offset:540
	ds_read_b32 v173, v165 offset:544
	ds_read_b32 v174, v165 offset:644
	ds_read_b32 v175, v165 offset:648
	ds_read_b32 v176, v165 offset:652
	ds_read_b32 v177, v165 offset:656
	ds_read_b32 v178, v165 offset:660
	ds_read_b32 v179, v165 offset:664
	ds_read_b32 v180, v165 offset:668
	ds_read_b32 v181, v165 offset:672
	s_waitcnt lgkmcnt(0)
	v_pk_add_f32 v[130:131], v[130:131], v[168:169]
	v_pk_add_f32 v[128:129], v[128:129], v[166:167]
	v_pk_add_f32 v[126:127], v[126:127], v[172:173]
	v_pk_add_f32 v[124:125], v[124:125], v[170:171]
	v_pk_add_f32 v[122:123], v[122:123], v[176:177]
	v_pk_add_f32 v[120:121], v[120:121], v[174:175]
	v_pk_add_f32 v[118:119], v[118:119], v[180:181]
	v_pk_add_f32 v[116:117], v[116:117], v[178:179]
